# v7 plus one in-loop copy slot per down-projection K-iteration taking 3/4 of the copy units that v7 left in the attention phase
# speedup vs baseline: 1.0412x; 1.0253x over previous
.LBB0_1209:
	v_readlane_b32 s10, v240, 0
	s_add_i32 s12, s8, s10
	s_lshl_b32 s8, s95, 8
	s_add_i32 s8, s8, s15
	s_ashr_i32 s9, s8, 7
	v_readlane_b32 s11, v240, 1
	s_mul_hi_i32 s10, s9, 0x55555556
	s_lshr_b32 s11, s10, 31
	s_add_i32 s10, s10, s11
	s_mul_i32 s11, s14, 3
	s_add_i32 s11, s10, s11
	s_mul_i32 s10, s10, 3
	s_mul_i32 s11, s11, 3
	s_sub_i32 s10, s9, s10
	s_add_i32 s11, s11, s10
	s_mul_hi_i32 s10, s8, 0x30c30c31
	s_lshr_b32 s16, s10, 31
	s_ashr_i32 s10, s10, 4
	s_add_i32 s10, s10, s16
	s_lshl_b32 s16, s10, 3
	s_or_b32 s16, s16, s14
	s_mulk_i32 s10, 0x54
	s_mulk_i32 s16, 0x54
	s_sub_i32 s10, s8, s10
	s_add_i32 s13, s12, 0x2a00
	s_add_i32 s96, s12, 0xffffed00
	s_add_i32 s16, s16, s10
	s_cmp_lt_u32 s9, 12
	s_cselect_b32 s10, s19, s2
	s_add_i32 s10, s10, s9
	s_cmp_lt_i32 s9, 9
	s_cselect_b32 s9, s11, s10
	s_lshl_b32 s9, s9, 7
	s_add_i32 s17, s9, s35
	s_cmpk_lt_i32 s8, 0x540
	s_cselect_b32 s10, s16, -1
	s_and_b64 s[8:9], s[58:59], exec
	s_cselect_b32 s16, s12, s10
	s_cmpk_gt_i32 s12, 0x29ff
	s_cselect_b64 s[8:9], -1, 0
	s_and_b64 s[10:11], s[8:9], exec
	s_cselect_b32 s97, -1, s16
	s_or_b64 s[8:9], s[8:9], s[58:59]
	s_cmpk_lt_u32 s96, 0x1800
	s_cselect_b64 s[10:11], -1, 0
	s_and_b64 s[74:75], s[8:9], s[10:11]
	s_and_b64 s[8:9], s[58:59], exec
	s_cselect_b32 s8, s13, s17
	s_cmpk_lt_i32 s12, 0x3800
	s_mov_b32 s40, s82
	s_cselect_b32 s52, s8, -1
	s_mov_b64 s[76:77], -1
	s_mov_b32 s10, s57
	s_branch .LBB0_1212

.LBB0_1723:
	s_and_b64 vcc, exec, s[4:5]
	s_cbranch_vccnz .LBB0_1763
	s_lshr_b32 s32, s69, 7
	s_lshl_b32 s32, s32, 3
	s_load_dwordx2 s[96:97], s[0:1], s32 offset:0x20
	s_load_dwordx2 s[72:73], s[0:1], 0xa0
	s_and_b32 s100, s69, 0x7f
	s_mul_i32 s100, s100, 0x300000
	s_mov_b32 s101, 0x1ee80000
	s_cmp_lt_u32 s69, 0x80
	s_cselect_b32 s101, 0x6e80000, s101
	v_and_b32_e32 v238, 63, v164
	v_lshlrev_b32_e32 v238, 4, v238
	v_readfirstlane_b32 s76, v164
	s_waitcnt lgkmcnt(0)
	s_add_u32 s96, s96, s100
	s_addc_u32 s97, s97, 0
	s_add_u32 s96, s96, 0x3000
	s_addc_u32 s97, s97, 0
	s_and_b32 s97, s97, 0xffff
	s_mov_b32 s98, 0x300000
	s_mov_b32 s99, 0x20000
	s_add_u32 s72, s72, s101
	s_addc_u32 s73, s73, 0
	s_add_u32 s72, s72, s100
	s_addc_u32 s73, s73, 0
	s_and_b32 s73, s73, 0xffff
	s_mov_b32 s74, 0x300000
	s_mov_b32 s75, 0x20000
	s_lshr_b32 s76, s76, 6
	s_mul_i32 s101, s76, 0x4800
	s_mul_i32 s100, s76, 1
	s_lshr_b32 s32, s76, 1
	s_mul_i32 s32, s32, 1
	s_add_u32 s100, s100, s32
	s_mul_i32 s100, s100, 0x3000
	s_add_u32 s101, s101, s100
	s_add_u32 s101, s101, 0x1e0000
	s_add_u32 s100, s101, 0x400
	s_and_b32 s32, s76, 1
	s_mul_i32 s32, s32, 6
	s_add_u32 s32, s32, 1
	s_mov_b32 s76, 18
	buffer_load_dwordx4 v[234:237], v238, s[96:99], s101 offen nt
	v_ashrrev_i32_e32 v1, 31, v164
	v_lshrrev_b32_e32 v1, 26, v1
	v_add_u32_e32 v1, v164, v1
	v_ashrrev_i32_e32 v8, 6, v1
	v_bfe_i32 v1, v164, 27, 1
	v_lshlrev_b32_e32 v0, 4, v164
	v_lshrrev_b32_e32 v1, 22, v1
	v_add_u32_e32 v1, v0, v1
	v_and_b32_e32 v1, 0xfffffc00, v1
	v_sub_u32_e32 v1, v0, v1
	v_lshrrev_b32_e32 v2, 4, v1
	v_bitop3_b32 v1, v2, v1, 32 bitop3:0x6c
	v_ashrrev_i32_e32 v3, 31, v1
	v_lshrrev_b32_e32 v3, 26, v3
	v_lshlrev_b32_e32 v2, 3, v8
	v_add_u32_e32 v3, v1, v3
	v_and_b32_e32 v2, -16, v2
	v_ashrrev_i32_e32 v10, 6, v3
	v_and_b32_e32 v3, 0xc0, v3
	v_add_u32_e32 v2, v10, v2
	v_lshlrev_b32_e32 v4, 5, v8
	v_sub_u32_e32 v1, v1, v3
	v_mov_b32_e32 v3, 1
	v_and_b32_e32 v9, 32, v4
	v_ashrrev_i16_sdwa v1, v3, sext(v1) dst_sel:DWORD dst_unused:UNUSED_PAD src0_sel:DWORD src1_sel:BYTE_0
	v_lshlrev_b32_e32 v4, 1, v2
	v_lshrrev_b32_e32 v5, 2, v2
	v_and_b32_e32 v6, 3, v10
	s_mov_b32 s3, 0xffffe0
	v_bfe_i32 v11, v1, 0, 16
	v_and_b32_e32 v4, 24, v4
	v_and_b32_e32 v5, 4, v5
	v_and_or_b32 v6, v2, s3, v6
	s_movk_i32 s6, 0xb00
	v_add_u32_e32 v1, v9, v11
	v_or3_b32 v4, v6, v5, v4
	v_mul_lo_u32 v2, v2, s6
	v_add_lshl_u32 v130, v1, v2, 1
	v_mul_u32_u24_e32 v2, 0xb00, v4
	v_add_u32_e32 v0, 0x2000, v0
	v_add_lshl_u32 v132, v2, v1, 1
	v_ashrrev_i32_e32 v1, 31, v0
	v_lshrrev_b32_e32 v1, 22, v1
	v_add_u32_e32 v1, v0, v1
	v_ashrrev_i32_e32 v12, 10, v1
	v_mul_i32_i24_e32 v1, 0x400, v12
	v_sub_u32_e32 v0, v0, v1
	v_lshrrev_b32_e32 v1, 4, v0
	v_bitop3_b32 v0, v1, v0, 32 bitop3:0x6c
	v_ashrrev_i32_e32 v2, 31, v0
	v_lshrrev_b32_e32 v2, 26, v2
	v_lshlrev_b32_e32 v1, 3, v12
	v_add_u32_e32 v2, v0, v2
	s_ashr_i32 s4, s2, 6
	v_and_b32_e32 v1, -16, v1
	v_ashrrev_i32_e32 v13, 6, v2
	v_and_b32_e32 v2, 0xc0, v2
	v_add_u32_e32 v1, v13, v1
	v_lshlrev_b32_e32 v4, 5, v12
	v_sub_u32_e32 v0, v0, v2
	s_ashr_i32 s5, s2, 8
	s_lshl_b32 s15, s4, 10
	s_mul_i32 s11, s14, 0x160000
	v_and_b32_e32 v14, 32, v4
	v_ashrrev_i16_sdwa v0, v3, sext(v0) dst_sel:DWORD dst_unused:UNUSED_PAD src0_sel:DWORD src1_sel:BYTE_0
	v_lshlrev_b32_e32 v2, 1, v1
	v_lshrrev_b32_e32 v3, 2, v1
	v_and_b32_e32 v4, 3, v13
	s_mul_hi_i32 s10, s14, 0x160000
	s_add_u32 s54, s90, s11
	v_bfe_i32 v15, v0, 0, 16
	v_and_b32_e32 v2, 24, v2
	v_and_b32_e32 v3, 4, v3
	v_and_or_b32 v4, v1, s3, v4
	s_addc_u32 s55, s91, s10
	s_add_i32 s18, s15, 0
	v_add_u32_e32 v0, v14, v15
	v_or3_b32 v2, v4, v3, v2
	v_mul_lo_u32 v1, v1, s6
	s_add_i32 m0, s18, 0x10000
	v_add_lshl_u32 v134, v0, v1, 1
	v_mul_u32_u24_e32 v1, 0xb00, v2
	global_load_lds_dwordx4 v132, s[54:55]
	s_add_i32 m0, s18, 0x12000
	v_add_lshl_u32 v136, v1, v0, 1
	s_add_u32 s10, s54, 0xb0000
	global_load_lds_dwordx4 v136, s[54:55]
	s_addc_u32 s11, s55, 0
	s_add_i32 m0, s18, 0x14000
	s_mul_i32 s7, s67, 0x160000
	global_load_lds_dwordx4 v132, s[10:11]
	s_add_i32 m0, s18, 0x16000
	s_mul_hi_i32 s3, s67, 0x160000
	s_add_u32 s52, s8, s7
	s_addc_u32 s53, s9, s3
	s_add_i32 s19, s18, 0x2000
	global_load_lds_dwordx4 v136, s[10:11]
	s_mov_b32 m0, s18
	s_add_u32 s10, s52, 0xb0000
	global_load_lds_dwordx4 v130, s[52:53]
	s_mov_b32 m0, s19
	s_addc_u32 s11, s53, 0
	s_add_i32 s35, s18, 0x4000
	global_load_lds_dwordx4 v134, s[52:53]
	s_mov_b32 m0, s35
	s_add_i32 s43, s18, 0x6000
	global_load_lds_dwordx4 v130, s[10:11]
	s_mov_b32 m0, s43
	v_mov_b32_e32 v139, 0
	global_load_lds_dwordx4 v134, s[10:11]
	v_mov_b32_e32 v133, v139
	v_mov_b32_e32 v137, v139
	v_mov_b32_e32 v131, v139
	v_mov_b32_e32 v135, v139
	s_cmp_eq_u32 s5, 1
	s_mov_b32 s3, 0
	v_lshl_add_u64 v[6:7], s[54:55], 0, v[132:133]
	v_lshl_add_u64 v[4:5], s[54:55], 0, v[136:137]
	v_lshl_add_u64 v[0:1], s[52:53], 0, v[130:131]
	s_cselect_b64 s[10:11], -1, 0
	s_cmp_lg_u32 s5, 1
	v_lshl_add_u64 v[2:3], s[52:53], 0, v[134:135]
	s_cbranch_scc1 .LBB0_1726
	s_barrier
